# delta_seq (prompt chains) rewritten by hand: the four 64x64x64 products per chunk on f32-operand matrix cores (v_mfma_f32_32x32x2_f32, exact f32, bf16 operands widened exactly), S kept in registers, o
# speedup vs baseline: 1.0691x; 1.0691x over previous
.LBB0_758:
	s_andn2_b64 vcc, exec, s[2:3]
	s_cbranch_vccnz .LBB0_527
	s_setprio 3
	s_mov_b32 s13, s21
	v_readlane_b32 s14, v255, 18
	v_readlane_b32 s16, v253, 0
	v_readlane_b32 s17, v253, 1
	s_nop 4
	s_load_dwordx2 s[2:3], s[16:17], -0x10
	s_load_dwordx2 s[20:21], s[16:17], -0xf0
	s_mov_b32 s34, 0xffff0000
	s_lshr_b32 s15, s13, 2
	s_and_b32 s54, s13, 3
	s_waitcnt lgkmcnt(0)
	s_lshl_b32 s55, s14, 3
	s_add_u32 s55, s55, s15
	s_lshl_b32 s55, s55, 16
	s_lshl_b32 s12, s54, 14
	s_add_u32 s55, s55, s12
	s_add_u32 s55, s55, 0x4400000
	s_add_u32 s30, s2, s55
	s_addc_u32 s31, s3, 0
	s_lshl_b32 s55, s14, 8
	s_add_u32 s20, s20, s55
	s_addc_u32 s21, s21, 0
	s_mul_i32 s55, s13, 0x14a000
	s_add_u32 s2, s2, s55
	s_addc_u32 s3, s3, 0
	s_mul_i32 s55, s13, 132
	s_add_u32 s55, s55, 0x400
	s_add_u32 s4, s50, s55
	s_addc_u32 s5, s51, 0
	s_mul_i32 s55, s15, 2064
	s_sub_u32 s55, s55, 48
	s_lshl_b32 s12, s55, 11
	s_ashr_i32 s9, s55, 21
	s_lshl_b32 s16, s54, 7
	s_add_u32 s12, s12, s16
	s_add_u32 s8, s50, 0xe629000
	s_addc_u32 s17, s51, s9
	s_add_u32 s8, s8, s12
	s_addc_u32 s9, s17, 0
	s_mul_i32 s12, s55, 4608
	s_mul_hi_i32 s11, s55, 4608
	s_add_u32 s16, s16, 1536
	s_add_u32 s12, s12, s16
	s_addc_u32 s11, s11, 0
	s_add_u32 s10, s50, 0x9919000
	s_addc_u32 s17, s51, s11
	s_add_u32 s10, s10, s12
	s_addc_u32 s11, s17, 0
	v_and_b32_e32 v185, 63, v216
	v_lshrrev_b32_e32 v186, 6, v216
	v_lshlrev_b32_e32 v165, 5, v216
	v_add_u32_e32 v166, 0x2000, v165
	v_add_u32_e32 v167, 0x4000, v165
	v_add_u32_e32 v168, 0x6000, v165
	v_add_u32_e32 v169, 0x8000, v165
	v_lshrrev_b32_e32 v187, 2, v216
	v_and_b32_e32 v188, 3, v216
	v_mul_u32_u24_e32 v187, 0x90, v187
	v_lshl_add_u32 v170, v188, 5, v187
	v_and_b32_e32 v187, 31, v185
	v_lshrrev_b32_e32 v188, 5, v185
	v_lshrrev_b32_e32 v189, 1, v186
	v_lshl_add_u32 v190, v189, 5, v187
	v_mul_u32_u24_e32 v190, 0x90, v190
	v_lshl_add_u32 v171, v188, 6, v190
	v_and_b32_e32 v191, 1, v186
	v_lshl_add_u32 v192, v191, 5, v187
	v_lshlrev_b32_e32 v193, 2, v192
	v_lshl_add_u32 v172, v188, 13, v193
	v_lshl_add_u32 v173, v188, 10, v193
	v_lshl_add_u32 v173, v189, 13, v173
	v_add_u32_e32 v184, 0x1000, v173
	v_lshlrev_b32_e32 v194, 3, v189
	v_add_u32_e32 v194, v194, v188
	v_mul_u32_u24_e32 v194, 0x240, v194
	v_lshl_add_u32 v174, v192, 1, v194
	v_lshrrev_b32_e32 v187, 4, v216
	v_and_b32_e32 v188, 15, v216
	v_lshlrev_b32_e32 v190, 4, v188
	v_lshl_add_u32 v175, v187, 8, v190
	v_lshlrev_b32_e32 v191, 3, v188
	v_lshl_add_u32 v176, v187, 11, v191
	v_mul_u32_u24_e32 v192, 0x1200, v187
	v_add_u32_e32 v180, v192, v191
	v_add_u32_e32 v177, 0x8000, v176
	v_add_u32_e32 v181, 0x12000, v180
	v_add_u32_e32 v178, 0x10000, v176
	v_add_u32_e32 v182, 0x24000, v180
	v_add_u32_e32 v179, 0x18000, v176
	v_add_u32_e32 v183, 0x36000, v180
	global_load_dwordx4 v[160:163], v190, s[20:21]
	v_mov_b32_e32 v0, 0
	v_mov_b32_e32 v1, 0
	v_mov_b32_e32 v2, 0
	v_mov_b32_e32 v3, 0
	v_mov_b32_e32 v4, 0
	v_mov_b32_e32 v5, 0
	v_mov_b32_e32 v6, 0
	v_mov_b32_e32 v7, 0
	v_mov_b32_e32 v8, 0
	v_mov_b32_e32 v9, 0
	v_mov_b32_e32 v10, 0
	v_mov_b32_e32 v11, 0
	v_mov_b32_e32 v12, 0
	v_mov_b32_e32 v13, 0
	v_mov_b32_e32 v14, 0
	v_mov_b32_e32 v15, 0
	v_lshlrev_b32_e32 v193, 6, v216
	ds_write_b128 v193, v[0:3] offset:0
	ds_write_b128 v193, v[0:3] offset:16
	ds_write_b128 v193, v[0:3] offset:32
	ds_write_b128 v193, v[0:3] offset:48
	global_load_dwordx4 v[112:115], v165, s[2:3]
	global_load_dwordx4 v[116:119], v165, s[2:3] offset:16
	global_load_dwordx4 v[120:123], v166, s[2:3]
	global_load_dwordx4 v[124:127], v166, s[2:3] offset:16
	global_load_dwordx4 v[128:131], v167, s[2:3]
	global_load_dwordx4 v[132:135], v167, s[2:3] offset:16
	global_load_dwordx4 v[136:139], v168, s[2:3]
	global_load_dwordx4 v[140:143], v168, s[2:3] offset:16
	global_load_dword v164, v201, s[4:5]
	global_load_dwordx2 v[158:159], v183, s[10:11]
	global_load_dwordx4 v[144:147], v169, s[2:3]
	global_load_dwordx4 v[148:151], v169, s[2:3] offset:16
	s_add_u32 s2, s2, 0xa000
	s_addc_u32 s3, s3, 0
	s_add_u32 s4, s4, 4
	s_addc_u32 s5, s5, 0
	s_add_u32 s10, s10, 0x48000
	s_addc_u32 s11, s11, 0
	s_mov_b32 s12, 0
	s_waitcnt vmcnt(0)
.Ldq_loop:
	s_waitcnt lgkmcnt(0)
	s_barrier
	ds_write_b128 v170, v[112:115] offset:60416
	ds_write_b128 v170, v[116:119] offset:60432
	ds_write_b128 v170, v[120:123] offset:32768
	ds_write_b128 v170, v[124:127] offset:32784
	ds_write_b128 v170, v[128:131] offset:41984
	ds_write_b128 v170, v[132:135] offset:42000
	ds_write_b128 v170, v[136:139] offset:51200
	ds_write_b128 v170, v[140:143] offset:51216
	s_waitcnt lgkmcnt(0)
	s_barrier
	s_cmp_eq_u32 s12, 32
	s_cbranch_scc1 .Ldq_nopf1
	global_load_dwordx4 v[112:115], v165, s[2:3]
	global_load_dwordx4 v[116:119], v165, s[2:3] offset:16
	global_load_dwordx4 v[120:123], v166, s[2:3]
	global_load_dwordx4 v[124:127], v166, s[2:3] offset:16
	global_load_dwordx4 v[128:131], v167, s[2:3]
	global_load_dwordx4 v[132:135], v167, s[2:3] offset:16
	global_load_dwordx4 v[136:139], v168, s[2:3]
	global_load_dwordx4 v[140:143], v168, s[2:3] offset:16
	global_load_dword v212, v201, s[4:5]
	global_load_dwordx2 v[204:205], v180, s[10:11]
	global_load_dwordx2 v[206:207], v181, s[10:11]
	global_load_dwordx2 v[208:209], v182, s[10:11]
	global_load_dwordx2 v[210:211], v183, s[10:11]
.Ldq_nopf1:
	ds_read_b128 v[96:99], v171 offset:32768
	ds_read_b128 v[100:103], v171 offset:32784
	ds_read_b128 v[104:107], v171 offset:32800
	ds_read_b128 v[108:111], v171 offset:32816
	s_waitcnt lgkmcnt(0)
	ds_read_b32 v64, v172 offset:0
	ds_read_b32 v65, v172 offset:256
	ds_read_b32 v66, v172 offset:512
	ds_read_b32 v67, v172 offset:768
	ds_read_b32 v68, v172 offset:1024
	ds_read_b32 v69, v172 offset:1280
	ds_read_b32 v70, v172 offset:1536
	ds_read_b32 v71, v172 offset:1792
	ds_read_b32 v72, v172 offset:2048
	ds_read_b32 v73, v172 offset:2304
	ds_read_b32 v74, v172 offset:2560
	ds_read_b32 v75, v172 offset:2816
	ds_read_b32 v76, v172 offset:3072
	ds_read_b32 v77, v172 offset:3328
	ds_read_b32 v78, v172 offset:3584
	v_lshlrev_b32_e32 v32, 16, v96
	v_and_b32_e32 v33, 0xffff0000, v96
	v_lshlrev_b32_e32 v34, 16, v97
	v_and_b32_e32 v35, 0xffff0000, v97
	v_lshlrev_b32_e32 v36, 16, v98
	v_and_b32_e32 v37, 0xffff0000, v98
	v_lshlrev_b32_e32 v38, 16, v99
	v_and_b32_e32 v39, 0xffff0000, v99
	v_lshlrev_b32_e32 v40, 16, v100
	v_and_b32_e32 v41, 0xffff0000, v100
	v_lshlrev_b32_e32 v42, 16, v101
	v_and_b32_e32 v43, 0xffff0000, v101
	v_lshlrev_b32_e32 v44, 16, v102
	v_and_b32_e32 v45, 0xffff0000, v102
	v_lshlrev_b32_e32 v46, 16, v103
	v_and_b32_e32 v47, 0xffff0000, v103
	v_lshlrev_b32_e32 v48, 16, v104
	v_and_b32_e32 v49, 0xffff0000, v104
	v_lshlrev_b32_e32 v50, 16, v105
	v_and_b32_e32 v51, 0xffff0000, v105
	v_lshlrev_b32_e32 v52, 16, v106
	v_and_b32_e32 v53, 0xffff0000, v106
	v_lshlrev_b32_e32 v54, 16, v107
	v_and_b32_e32 v55, 0xffff0000, v107
	v_lshlrev_b32_e32 v56, 16, v108
	v_and_b32_e32 v57, 0xffff0000, v108
	v_lshlrev_b32_e32 v58, 16, v109
	v_and_b32_e32 v59, 0xffff0000, v109
	v_lshlrev_b32_e32 v60, 16, v110
	v_and_b32_e32 v61, 0xffff0000, v110
	v_lshlrev_b32_e32 v62, 16, v111
	v_and_b32_e32 v63, 0xffff0000, v111
	s_waitcnt lgkmcnt(0)
	ds_read_b32 v79, v172 offset:3840
	ds_read_b32 v80, v172 offset:4096
	ds_read_b32 v81, v172 offset:4352
	ds_read_b32 v82, v172 offset:4608
	ds_read_b32 v83, v172 offset:4864
	ds_read_b32 v84, v172 offset:5120
	ds_read_b32 v85, v172 offset:5376
	ds_read_b32 v86, v172 offset:5632
	ds_read_b32 v87, v172 offset:5888
	ds_read_b32 v88, v172 offset:6144
	ds_read_b32 v89, v172 offset:6400
	ds_read_b32 v90, v172 offset:6656
	ds_read_b32 v91, v172 offset:6912
	ds_read_b32 v92, v172 offset:7168
	ds_read_b32 v93, v172 offset:7424
	v_mfma_f32_32x32x2_f32 v[16:31], v32, v64, 0
	v_mfma_f32_32x32x2_f32 v[16:31], v33, v65, v[16:31]
	v_mfma_f32_32x32x2_f32 v[16:31], v34, v66, v[16:31]
	v_mfma_f32_32x32x2_f32 v[16:31], v35, v67, v[16:31]
	v_mfma_f32_32x32x2_f32 v[16:31], v36, v68, v[16:31]
	v_mfma_f32_32x32x2_f32 v[16:31], v37, v69, v[16:31]
	v_mfma_f32_32x32x2_f32 v[16:31], v38, v70, v[16:31]
	v_mfma_f32_32x32x2_f32 v[16:31], v39, v71, v[16:31]
	v_mfma_f32_32x32x2_f32 v[16:31], v40, v72, v[16:31]
	v_mfma_f32_32x32x2_f32 v[16:31], v41, v73, v[16:31]
	v_mfma_f32_32x32x2_f32 v[16:31], v42, v74, v[16:31]
	v_mfma_f32_32x32x2_f32 v[16:31], v43, v75, v[16:31]
	v_mfma_f32_32x32x2_f32 v[16:31], v44, v76, v[16:31]
	v_mfma_f32_32x32x2_f32 v[16:31], v45, v77, v[16:31]
	v_mfma_f32_32x32x2_f32 v[16:31], v46, v78, v[16:31]
	s_waitcnt lgkmcnt(0)
	ds_read_b32 v94, v172 offset:7680
	ds_read_b32 v95, v172 offset:7936
	v_mfma_f32_32x32x2_f32 v[16:31], v47, v79, v[16:31]
	v_mfma_f32_32x32x2_f32 v[16:31], v48, v80, v[16:31]
	v_mfma_f32_32x32x2_f32 v[16:31], v49, v81, v[16:31]
	v_mfma_f32_32x32x2_f32 v[16:31], v50, v82, v[16:31]
	v_mfma_f32_32x32x2_f32 v[16:31], v51, v83, v[16:31]
	v_mfma_f32_32x32x2_f32 v[16:31], v52, v84, v[16:31]
	v_mfma_f32_32x32x2_f32 v[16:31], v53, v85, v[16:31]
	v_mfma_f32_32x32x2_f32 v[16:31], v54, v86, v[16:31]
	v_mfma_f32_32x32x2_f32 v[16:31], v55, v87, v[16:31]
	v_mfma_f32_32x32x2_f32 v[16:31], v56, v88, v[16:31]
	v_mfma_f32_32x32x2_f32 v[16:31], v57, v89, v[16:31]
	v_mfma_f32_32x32x2_f32 v[16:31], v58, v90, v[16:31]
	v_mfma_f32_32x32x2_f32 v[16:31], v59, v91, v[16:31]
	v_mfma_f32_32x32x2_f32 v[16:31], v60, v92, v[16:31]
	v_mfma_f32_32x32x2_f32 v[16:31], v61, v93, v[16:31]
	s_waitcnt lgkmcnt(0)
	v_mfma_f32_32x32x2_f32 v[16:31], v62, v94, v[16:31]
	v_mfma_f32_32x32x2_f32 v[16:31], v63, v95, v[16:31]
	ds_read_u16 v96, v174 offset:60416
	ds_read_u16 v97, v174 offset:60560
	ds_read_u16 v98, v174 offset:60704
	ds_read_u16 v99, v174 offset:60848
	ds_read_u16 v100, v174 offset:61568
	ds_read_u16 v101, v174 offset:61712
	ds_read_u16 v102, v174 offset:61856
	ds_read_u16 v103, v174 offset:62000
	ds_read_u16 v104, v174 offset:62720
	ds_read_u16 v105, v174 offset:62864
	ds_read_u16 v106, v174 offset:63008
	ds_read_u16 v107, v174 offset:63152
	ds_read_u16 v108, v174 offset:63872
	ds_read_u16 v109, v174 offset:64016
	ds_read_u16 v110, v174 offset:64160
	ds_read_u16 v111, v174 offset:64304
	s_waitcnt lgkmcnt(0)
	s_nop 7
	s_nop 7
	s_nop 3
	v_lshlrev_b32_e32 v96, 16, v96
	v_lshlrev_b32_e32 v97, 16, v97
	v_lshlrev_b32_e32 v98, 16, v98
	v_lshlrev_b32_e32 v99, 16, v99
	v_lshlrev_b32_e32 v100, 16, v100
	v_lshlrev_b32_e32 v101, 16, v101
	v_lshlrev_b32_e32 v102, 16, v102
	v_lshlrev_b32_e32 v103, 16, v103
	v_lshlrev_b32_e32 v104, 16, v104
	v_lshlrev_b32_e32 v105, 16, v105
	v_lshlrev_b32_e32 v106, 16, v106
	v_lshlrev_b32_e32 v107, 16, v107
	v_lshlrev_b32_e32 v108, 16, v108
	v_lshlrev_b32_e32 v109, 16, v109
	v_lshlrev_b32_e32 v110, 16, v110
	v_lshlrev_b32_e32 v111, 16, v111
	v_sub_f32_e32 v96, v96, v16
	v_sub_f32_e32 v97, v97, v17
	v_sub_f32_e32 v98, v98, v18
	v_sub_f32_e32 v99, v99, v19
	v_sub_f32_e32 v100, v100, v20
	v_sub_f32_e32 v101, v101, v21
	v_sub_f32_e32 v102, v102, v22
	v_sub_f32_e32 v103, v103, v23
	v_sub_f32_e32 v104, v104, v24
	v_sub_f32_e32 v105, v105, v25
	v_sub_f32_e32 v106, v106, v26
	v_sub_f32_e32 v107, v107, v27
	v_sub_f32_e32 v108, v108, v28
	v_sub_f32_e32 v109, v109, v29
	v_sub_f32_e32 v110, v110, v30
	v_sub_f32_e32 v111, v111, v31
	ds_write_b32 v173, v96 offset:16384
	ds_write_b32 v173, v97 offset:16640
	ds_write_b32 v173, v98 offset:16896
	ds_write_b32 v173, v99 offset:17152
	ds_write_b32 v173, v100 offset:18432
	ds_write_b32 v173, v101 offset:18688
	ds_write_b32 v173, v102 offset:18944
	ds_write_b32 v173, v103 offset:19200
	ds_write_b32 v173, v104 offset:20480
	ds_write_b32 v173, v105 offset:20736
	ds_write_b32 v173, v106 offset:20992
	ds_write_b32 v173, v107 offset:21248
	ds_write_b32 v173, v108 offset:22528
	ds_write_b32 v173, v109 offset:22784
	ds_write_b32 v173, v110 offset:23040
	ds_write_b32 v173, v111 offset:23296
	s_waitcnt lgkmcnt(0)
	s_barrier
	ds_write_b128 v170, v[144:147] offset:32768
	ds_write_b128 v170, v[148:151] offset:32784
	s_cmp_eq_u32 s12, 32
	s_cbranch_scc1 .Ldq_nopf2
	s_nop 1
	global_load_dwordx4 v[144:147], v169, s[2:3]
	global_load_dwordx4 v[148:151], v169, s[2:3] offset:16
	s_add_u32 s2, s2, 0xa000
	s_addc_u32 s3, s3, 0
	s_add_u32 s4, s4, 4
	s_addc_u32 s5, s5, 0
	s_add_u32 s10, s10, 0x48000
	s_addc_u32 s11, s11, 0
.Ldq_nopf2:
	ds_read_b128 v[96:99], v171 offset:41984
	ds_read_b128 v[100:103], v171 offset:42000
	ds_read_b128 v[104:107], v171 offset:42016
	ds_read_b128 v[108:111], v171 offset:42032
	s_waitcnt lgkmcnt(0)
	ds_read_b32 v64, v172 offset:0
	ds_read_b32 v65, v172 offset:256
	ds_read_b32 v66, v172 offset:512
	ds_read_b32 v67, v172 offset:768
	ds_read_b32 v68, v172 offset:1024
	ds_read_b32 v69, v172 offset:1280
	ds_read_b32 v70, v172 offset:1536
	ds_read_b32 v71, v172 offset:1792
	ds_read_b32 v72, v172 offset:2048
	ds_read_b32 v73, v172 offset:2304
	ds_read_b32 v74, v172 offset:2560
	ds_read_b32 v75, v172 offset:2816
	ds_read_b32 v76, v172 offset:3072
	ds_read_b32 v77, v172 offset:3328
	ds_read_b32 v78, v172 offset:3584
	v_lshlrev_b32_e32 v32, 16, v96
	v_and_b32_e32 v33, 0xffff0000, v96
	v_lshlrev_b32_e32 v34, 16, v97
	v_and_b32_e32 v35, 0xffff0000, v97
	v_lshlrev_b32_e32 v36, 16, v98
	v_and_b32_e32 v37, 0xffff0000, v98
	v_lshlrev_b32_e32 v38, 16, v99
	v_and_b32_e32 v39, 0xffff0000, v99
	v_lshlrev_b32_e32 v40, 16, v100
	v_and_b32_e32 v41, 0xffff0000, v100
	v_lshlrev_b32_e32 v42, 16, v101
	v_and_b32_e32 v43, 0xffff0000, v101
	v_lshlrev_b32_e32 v44, 16, v102
	v_and_b32_e32 v45, 0xffff0000, v102
	v_lshlrev_b32_e32 v46, 16, v103
	v_and_b32_e32 v47, 0xffff0000, v103
	v_lshlrev_b32_e32 v48, 16, v104
	v_and_b32_e32 v49, 0xffff0000, v104
	v_lshlrev_b32_e32 v50, 16, v105
	v_and_b32_e32 v51, 0xffff0000, v105
	v_lshlrev_b32_e32 v52, 16, v106
	v_and_b32_e32 v53, 0xffff0000, v106
	v_lshlrev_b32_e32 v54, 16, v107
	v_and_b32_e32 v55, 0xffff0000, v107
	v_lshlrev_b32_e32 v56, 16, v108
	v_and_b32_e32 v57, 0xffff0000, v108
	v_lshlrev_b32_e32 v58, 16, v109
	v_and_b32_e32 v59, 0xffff0000, v109
	v_lshlrev_b32_e32 v60, 16, v110
	v_and_b32_e32 v61, 0xffff0000, v110
	v_lshlrev_b32_e32 v62, 16, v111
	v_and_b32_e32 v63, 0xffff0000, v111
	s_waitcnt lgkmcnt(0)
	ds_read_b32 v79, v172 offset:3840
	ds_read_b32 v80, v172 offset:4096
	ds_read_b32 v81, v172 offset:4352
	ds_read_b32 v82, v172 offset:4608
	ds_read_b32 v83, v172 offset:4864
	ds_read_b32 v84, v172 offset:5120
	ds_read_b32 v85, v172 offset:5376
	ds_read_b32 v86, v172 offset:5632
	ds_read_b32 v87, v172 offset:5888
	ds_read_b32 v88, v172 offset:6144
	ds_read_b32 v89, v172 offset:6400
	ds_read_b32 v90, v172 offset:6656
	ds_read_b32 v91, v172 offset:6912
	ds_read_b32 v92, v172 offset:7168
	ds_read_b32 v93, v172 offset:7424
	v_mfma_f32_32x32x2_f32 v[16:31], v32, v64, 0
	v_mfma_f32_32x32x2_f32 v[16:31], v33, v65, v[16:31]
	v_mfma_f32_32x32x2_f32 v[16:31], v34, v66, v[16:31]
	v_mfma_f32_32x32x2_f32 v[16:31], v35, v67, v[16:31]
	v_mfma_f32_32x32x2_f32 v[16:31], v36, v68, v[16:31]
	v_mfma_f32_32x32x2_f32 v[16:31], v37, v69, v[16:31]
	v_mfma_f32_32x32x2_f32 v[16:31], v38, v70, v[16:31]
	v_mfma_f32_32x32x2_f32 v[16:31], v39, v71, v[16:31]
	v_mfma_f32_32x32x2_f32 v[16:31], v40, v72, v[16:31]
	v_mfma_f32_32x32x2_f32 v[16:31], v41, v73, v[16:31]
	v_mfma_f32_32x32x2_f32 v[16:31], v42, v74, v[16:31]
	v_mfma_f32_32x32x2_f32 v[16:31], v43, v75, v[16:31]
	v_mfma_f32_32x32x2_f32 v[16:31], v44, v76, v[16:31]
	v_mfma_f32_32x32x2_f32 v[16:31], v45, v77, v[16:31]
	v_mfma_f32_32x32x2_f32 v[16:31], v46, v78, v[16:31]
	s_waitcnt lgkmcnt(0)
	ds_read_b32 v94, v172 offset:7680
	ds_read_b32 v95, v172 offset:7936
	v_mfma_f32_32x32x2_f32 v[16:31], v47, v79, v[16:31]
	v_mfma_f32_32x32x2_f32 v[16:31], v48, v80, v[16:31]
	v_mfma_f32_32x32x2_f32 v[16:31], v49, v81, v[16:31]
	v_mfma_f32_32x32x2_f32 v[16:31], v50, v82, v[16:31]
	v_mfma_f32_32x32x2_f32 v[16:31], v51, v83, v[16:31]
	v_mfma_f32_32x32x2_f32 v[16:31], v52, v84, v[16:31]
	v_mfma_f32_32x32x2_f32 v[16:31], v53, v85, v[16:31]
	v_mfma_f32_32x32x2_f32 v[16:31], v54, v86, v[16:31]
	v_mfma_f32_32x32x2_f32 v[16:31], v55, v87, v[16:31]
	v_mfma_f32_32x32x2_f32 v[16:31], v56, v88, v[16:31]
	v_mfma_f32_32x32x2_f32 v[16:31], v57, v89, v[16:31]
	v_mfma_f32_32x32x2_f32 v[16:31], v58, v90, v[16:31]
	v_mfma_f32_32x32x2_f32 v[16:31], v59, v91, v[16:31]
	v_mfma_f32_32x32x2_f32 v[16:31], v60, v92, v[16:31]
	v_mfma_f32_32x32x2_f32 v[16:31], v61, v93, v[16:31]
	s_waitcnt lgkmcnt(0)
	v_mfma_f32_32x32x2_f32 v[16:31], v62, v94, v[16:31]
	v_mfma_f32_32x32x2_f32 v[16:31], v63, v95, v[16:31]
	ds_read_b128 v[96:99], v171 offset:51200
	ds_read_b128 v[100:103], v171 offset:51216
	ds_read_b128 v[104:107], v171 offset:51232
	ds_read_b128 v[108:111], v171 offset:51248
	s_waitcnt lgkmcnt(0)
	ds_read_b32 v64, v172 offset:16384
	ds_read_b32 v65, v172 offset:16640
	ds_read_b32 v66, v172 offset:16896
	ds_read_b32 v67, v172 offset:17152
	ds_read_b32 v68, v172 offset:17408
	ds_read_b32 v69, v172 offset:17664
	ds_read_b32 v70, v172 offset:17920
	ds_read_b32 v71, v172 offset:18176
	ds_read_b32 v72, v172 offset:18432
	ds_read_b32 v73, v172 offset:18688
	ds_read_b32 v74, v172 offset:18944
	ds_read_b32 v75, v172 offset:19200
	ds_read_b32 v76, v172 offset:19456
	ds_read_b32 v77, v172 offset:19712
	ds_read_b32 v78, v172 offset:19968
	v_lshlrev_b32_e32 v32, 16, v96
	v_and_b32_e32 v33, 0xffff0000, v96
	v_lshlrev_b32_e32 v34, 16, v97
	v_and_b32_e32 v35, 0xffff0000, v97
	v_lshlrev_b32_e32 v36, 16, v98
	v_and_b32_e32 v37, 0xffff0000, v98
	v_lshlrev_b32_e32 v38, 16, v99
	v_and_b32_e32 v39, 0xffff0000, v99
	v_lshlrev_b32_e32 v40, 16, v100
	v_and_b32_e32 v41, 0xffff0000, v100
	v_lshlrev_b32_e32 v42, 16, v101
	v_and_b32_e32 v43, 0xffff0000, v101
	v_lshlrev_b32_e32 v44, 16, v102
	v_and_b32_e32 v45, 0xffff0000, v102
	v_lshlrev_b32_e32 v46, 16, v103
	v_and_b32_e32 v47, 0xffff0000, v103
	v_lshlrev_b32_e32 v48, 16, v104
	v_and_b32_e32 v49, 0xffff0000, v104
	v_lshlrev_b32_e32 v50, 16, v105
	v_and_b32_e32 v51, 0xffff0000, v105
	v_lshlrev_b32_e32 v52, 16, v106
	v_and_b32_e32 v53, 0xffff0000, v106
	v_lshlrev_b32_e32 v54, 16, v107
	v_and_b32_e32 v55, 0xffff0000, v107
	v_lshlrev_b32_e32 v56, 16, v108
	v_and_b32_e32 v57, 0xffff0000, v108
	v_lshlrev_b32_e32 v58, 16, v109
	v_and_b32_e32 v59, 0xffff0000, v109
	v_lshlrev_b32_e32 v60, 16, v110
	v_and_b32_e32 v61, 0xffff0000, v110
	v_lshlrev_b32_e32 v62, 16, v111
	v_and_b32_e32 v63, 0xffff0000, v111
	s_waitcnt lgkmcnt(0)
	ds_read_b32 v79, v172 offset:20224
	ds_read_b32 v80, v172 offset:20480
	ds_read_b32 v81, v172 offset:20736
	ds_read_b32 v82, v172 offset:20992
	ds_read_b32 v83, v172 offset:21248
	ds_read_b32 v84, v172 offset:21504
	ds_read_b32 v85, v172 offset:21760
	ds_read_b32 v86, v172 offset:22016
	ds_read_b32 v87, v172 offset:22272
	ds_read_b32 v88, v172 offset:22528
	ds_read_b32 v89, v172 offset:22784
	ds_read_b32 v90, v172 offset:23040
	ds_read_b32 v91, v172 offset:23296
	ds_read_b32 v92, v172 offset:23552
	ds_read_b32 v93, v172 offset:23808
	v_mfma_f32_32x32x2_f32 v[16:31], v32, v64, v[16:31]
	v_mfma_f32_32x32x2_f32 v[16:31], v33, v65, v[16:31]
	v_mfma_f32_32x32x2_f32 v[16:31], v34, v66, v[16:31]
	v_mfma_f32_32x32x2_f32 v[16:31], v35, v67, v[16:31]
	v_mfma_f32_32x32x2_f32 v[16:31], v36, v68, v[16:31]
	v_mfma_f32_32x32x2_f32 v[16:31], v37, v69, v[16:31]
	v_mfma_f32_32x32x2_f32 v[16:31], v38, v70, v[16:31]
	v_mfma_f32_32x32x2_f32 v[16:31], v39, v71, v[16:31]
	v_mfma_f32_32x32x2_f32 v[16:31], v40, v72, v[16:31]
	v_mfma_f32_32x32x2_f32 v[16:31], v41, v73, v[16:31]
	v_mfma_f32_32x32x2_f32 v[16:31], v42, v74, v[16:31]
	v_mfma_f32_32x32x2_f32 v[16:31], v43, v75, v[16:31]
	v_mfma_f32_32x32x2_f32 v[16:31], v44, v76, v[16:31]
	v_mfma_f32_32x32x2_f32 v[16:31], v45, v77, v[16:31]
	v_mfma_f32_32x32x2_f32 v[16:31], v46, v78, v[16:31]
	s_waitcnt lgkmcnt(0)
	ds_read_b32 v94, v172 offset:24064
	ds_read_b32 v95, v172 offset:24320
	v_mfma_f32_32x32x2_f32 v[16:31], v47, v79, v[16:31]
	v_mfma_f32_32x32x2_f32 v[16:31], v48, v80, v[16:31]
	v_mfma_f32_32x32x2_f32 v[16:31], v49, v81, v[16:31]
	v_mfma_f32_32x32x2_f32 v[16:31], v50, v82, v[16:31]
	v_mfma_f32_32x32x2_f32 v[16:31], v51, v83, v[16:31]
	v_mfma_f32_32x32x2_f32 v[16:31], v52, v84, v[16:31]
	v_mfma_f32_32x32x2_f32 v[16:31], v53, v85, v[16:31]
	v_mfma_f32_32x32x2_f32 v[16:31], v54, v86, v[16:31]
	v_mfma_f32_32x32x2_f32 v[16:31], v55, v87, v[16:31]
	v_mfma_f32_32x32x2_f32 v[16:31], v56, v88, v[16:31]
	v_mfma_f32_32x32x2_f32 v[16:31], v57, v89, v[16:31]
	v_mfma_f32_32x32x2_f32 v[16:31], v58, v90, v[16:31]
	v_mfma_f32_32x32x2_f32 v[16:31], v59, v91, v[16:31]
	v_mfma_f32_32x32x2_f32 v[16:31], v60, v92, v[16:31]
	v_mfma_f32_32x32x2_f32 v[16:31], v61, v93, v[16:31]
	s_waitcnt lgkmcnt(0)
	v_mfma_f32_32x32x2_f32 v[16:31], v62, v94, v[16:31]
	v_mfma_f32_32x32x2_f32 v[16:31], v63, v95, v[16:31]
	s_waitcnt lgkmcnt(0)
	s_barrier
	s_nop 7
	s_nop 7
	s_nop 3
	ds_write_b32 v173, v16 offset:41984
	ds_write_b32 v173, v17 offset:42240
	ds_write_b32 v173, v18 offset:42496
	ds_write_b32 v173, v19 offset:42752
	ds_write_b32 v173, v20 offset:44032
	ds_write_b32 v173, v21 offset:44288
	ds_write_b32 v173, v22 offset:44544
	ds_write_b32 v173, v23 offset:44800
	ds_write_b32 v173, v24 offset:46080
	ds_write_b32 v173, v25 offset:46336
	ds_write_b32 v173, v26 offset:46592
	ds_write_b32 v173, v27 offset:46848
	ds_write_b32 v173, v28 offset:48128
	ds_write_b32 v173, v29 offset:48384
	ds_write_b32 v173, v30 offset:48640
	ds_write_b32 v173, v31 offset:48896
	ds_read_b128 v[96:99], v171 offset:32768
	ds_read_b128 v[100:103], v171 offset:32784
	ds_read_b128 v[104:107], v171 offset:32800
	ds_read_b128 v[108:111], v171 offset:32816
	s_waitcnt lgkmcnt(0)
	ds_read_b32 v64, v172 offset:16384
	ds_read_b32 v65, v172 offset:16640
	ds_read_b32 v66, v172 offset:16896
	ds_read_b32 v67, v172 offset:17152
	ds_read_b32 v68, v172 offset:17408
	ds_read_b32 v69, v172 offset:17664
	ds_read_b32 v70, v172 offset:17920
	ds_read_b32 v71, v172 offset:18176
	ds_read_b32 v72, v172 offset:18432
	ds_read_b32 v73, v172 offset:18688
	ds_read_b32 v74, v172 offset:18944
	ds_read_b32 v75, v172 offset:19200
	ds_read_b32 v76, v172 offset:19456
	ds_read_b32 v77, v172 offset:19712
	ds_read_b32 v78, v172 offset:19968
	v_lshlrev_b32_e32 v32, 16, v96
	v_and_b32_e32 v33, 0xffff0000, v96
	v_lshlrev_b32_e32 v34, 16, v97
	v_and_b32_e32 v35, 0xffff0000, v97
	v_lshlrev_b32_e32 v36, 16, v98
	v_and_b32_e32 v37, 0xffff0000, v98
	v_lshlrev_b32_e32 v38, 16, v99
	v_and_b32_e32 v39, 0xffff0000, v99
	v_lshlrev_b32_e32 v40, 16, v100
	v_and_b32_e32 v41, 0xffff0000, v100
	v_lshlrev_b32_e32 v42, 16, v101
	v_and_b32_e32 v43, 0xffff0000, v101
	v_lshlrev_b32_e32 v44, 16, v102
	v_and_b32_e32 v45, 0xffff0000, v102
	v_lshlrev_b32_e32 v46, 16, v103
	v_and_b32_e32 v47, 0xffff0000, v103
	v_lshlrev_b32_e32 v48, 16, v104
	v_and_b32_e32 v49, 0xffff0000, v104
	v_lshlrev_b32_e32 v50, 16, v105
	v_and_b32_e32 v51, 0xffff0000, v105
	v_lshlrev_b32_e32 v52, 16, v106
	v_and_b32_e32 v53, 0xffff0000, v106
	v_lshlrev_b32_e32 v54, 16, v107
	v_and_b32_e32 v55, 0xffff0000, v107
	v_lshlrev_b32_e32 v56, 16, v108
	v_and_b32_e32 v57, 0xffff0000, v108
	v_lshlrev_b32_e32 v58, 16, v109
	v_and_b32_e32 v59, 0xffff0000, v109
	v_lshlrev_b32_e32 v60, 16, v110
	v_and_b32_e32 v61, 0xffff0000, v110
	v_lshlrev_b32_e32 v62, 16, v111
	v_and_b32_e32 v63, 0xffff0000, v111
	s_waitcnt lgkmcnt(0)
	ds_read_b32 v79, v172 offset:20224
	ds_read_b32 v80, v172 offset:20480
	ds_read_b32 v81, v172 offset:20736
	ds_read_b32 v82, v172 offset:20992
	ds_read_b32 v83, v172 offset:21248
	ds_read_b32 v84, v172 offset:21504
	ds_read_b32 v85, v172 offset:21760
	ds_read_b32 v86, v172 offset:22016
	ds_read_b32 v87, v172 offset:22272
	ds_read_b32 v88, v172 offset:22528
	ds_read_b32 v89, v172 offset:22784
	ds_read_b32 v90, v172 offset:23040
	ds_read_b32 v91, v172 offset:23296
	ds_read_b32 v92, v172 offset:23552
	ds_read_b32 v93, v172 offset:23808
	v_mfma_f32_32x32x2_f32 v[16:31], v32, v64, 0
	v_mfma_f32_32x32x2_f32 v[16:31], v33, v65, v[16:31]
	v_mfma_f32_32x32x2_f32 v[16:31], v34, v66, v[16:31]
	v_mfma_f32_32x32x2_f32 v[16:31], v35, v67, v[16:31]
	v_mfma_f32_32x32x2_f32 v[16:31], v36, v68, v[16:31]
	v_mfma_f32_32x32x2_f32 v[16:31], v37, v69, v[16:31]
	v_mfma_f32_32x32x2_f32 v[16:31], v38, v70, v[16:31]
	v_mfma_f32_32x32x2_f32 v[16:31], v39, v71, v[16:31]
	v_mfma_f32_32x32x2_f32 v[16:31], v40, v72, v[16:31]
	v_mfma_f32_32x32x2_f32 v[16:31], v41, v73, v[16:31]
	v_mfma_f32_32x32x2_f32 v[16:31], v42, v74, v[16:31]
	v_mfma_f32_32x32x2_f32 v[16:31], v43, v75, v[16:31]
	v_mfma_f32_32x32x2_f32 v[16:31], v44, v76, v[16:31]
	v_mfma_f32_32x32x2_f32 v[16:31], v45, v77, v[16:31]
	v_mfma_f32_32x32x2_f32 v[16:31], v46, v78, v[16:31]
	s_waitcnt lgkmcnt(0)
	ds_read_b32 v94, v172 offset:24064
	ds_read_b32 v95, v172 offset:24320
	v_mfma_f32_32x32x2_f32 v[16:31], v47, v79, v[16:31]
	v_mfma_f32_32x32x2_f32 v[16:31], v48, v80, v[16:31]
	v_mfma_f32_32x32x2_f32 v[16:31], v49, v81, v[16:31]
	v_mfma_f32_32x32x2_f32 v[16:31], v50, v82, v[16:31]
	v_mfma_f32_32x32x2_f32 v[16:31], v51, v83, v[16:31]
	v_mfma_f32_32x32x2_f32 v[16:31], v52, v84, v[16:31]
	v_mfma_f32_32x32x2_f32 v[16:31], v53, v85, v[16:31]
	v_mfma_f32_32x32x2_f32 v[16:31], v54, v86, v[16:31]
	v_mfma_f32_32x32x2_f32 v[16:31], v55, v87, v[16:31]
	v_mfma_f32_32x32x2_f32 v[16:31], v56, v88, v[16:31]
	v_mfma_f32_32x32x2_f32 v[16:31], v57, v89, v[16:31]
	v_mfma_f32_32x32x2_f32 v[16:31], v58, v90, v[16:31]
	v_mfma_f32_32x32x2_f32 v[16:31], v59, v91, v[16:31]
	v_mfma_f32_32x32x2_f32 v[16:31], v60, v92, v[16:31]
	v_mfma_f32_32x32x2_f32 v[16:31], v61, v93, v[16:31]
	s_waitcnt lgkmcnt(0)
	v_mfma_f32_32x32x2_f32 v[16:31], v62, v94, v[16:31]
	v_mfma_f32_32x32x2_f32 v[16:31], v63, v95, v[16:31]
	s_nop 7
	s_nop 7
	s_nop 3
	v_fma_f32 v0, v164, v0, v16
	v_fma_f32 v1, v164, v1, v17
	v_fma_f32 v2, v164, v2, v18
	v_fma_f32 v3, v164, v3, v19
	v_fma_f32 v4, v164, v4, v20
	v_fma_f32 v5, v164, v5, v21
	v_fma_f32 v6, v164, v6, v22
	v_fma_f32 v7, v164, v7, v23
	v_fma_f32 v8, v164, v8, v24
	v_fma_f32 v9, v164, v9, v25
	v_fma_f32 v10, v164, v10, v26
	v_fma_f32 v11, v164, v11, v27
	v_fma_f32 v12, v164, v12, v28
	v_fma_f32 v13, v164, v13, v29
	v_fma_f32 v14, v164, v14, v30
	v_fma_f32 v15, v164, v15, v31
	ds_write_b32 v173, v0 offset:0
	ds_write_b32 v173, v1 offset:256
	ds_write_b32 v173, v2 offset:512
	ds_write_b32 v173, v3 offset:768
	ds_write_b32 v173, v4 offset:2048
	ds_write_b32 v173, v5 offset:2304
	ds_write_b32 v173, v6 offset:2560
	ds_write_b32 v173, v7 offset:2816
	ds_write_b32 v173, v8 offset:4096
	ds_write_b32 v173, v9 offset:4352
	ds_write_b32 v173, v10 offset:4608
	ds_write_b32 v173, v11 offset:4864
	ds_write_b32 v173, v12 offset:6144
	ds_write_b32 v173, v13 offset:6400
	ds_write_b32 v173, v14 offset:6656
	ds_write_b32 v173, v15 offset:6912
	s_waitcnt lgkmcnt(0)
	s_barrier
	s_cmp_eq_u32 s12, 0
	s_cbranch_scc1 .Ldq_epi3
	ds_read_b128 v[32:35], v175 offset:41984
	s_waitcnt lgkmcnt(0)
	v_mul_f32_e32 v185, v32, v32
	v_fmac_f32_e32 v185, v33, v33
	v_fmac_f32_e32 v185, v34, v34
	v_fmac_f32_e32 v185, v35, v35
	s_nop 1
	v_add_f32_dpp v185, v185, v185 quad_perm:[1,0,3,2] row_mask:0xf bank_mask:0xf
	s_nop 1
	v_add_f32_dpp v185, v185, v185 quad_perm:[2,3,0,1] row_mask:0xf bank_mask:0xf
	s_nop 1
	v_add_f32_dpp v185, v185, v185 row_half_mirror row_mask:0xf bank_mask:0xf
	s_nop 1
	v_add_f32_dpp v185, v185, v185 row_mirror row_mask:0xf bank_mask:0xf
	v_mov_b32_e32 v186, 0x358637bd
	v_fmac_f32_e32 v186, 0x3c800000, v185
	v_rsq_f32_e32 v186, v186
	s_nop 0
	v_mul_f32_e32 v32, v32, v186
	v_mul_f32_e32 v33, v33, v186
	v_mul_f32_e32 v34, v34, v186
	v_mul_f32_e32 v35, v35, v186
	v_mul_f32_e32 v32, v32, v160
	v_mul_f32_e32 v33, v33, v161
	v_mul_f32_e32 v34, v34, v162
	v_mul_f32_e32 v35, v35, v163
	v_lshlrev_b32_e32 v187, 16, v152
	v_and_b32_e32 v188, 0xffff0000, v152
	v_lshlrev_b32_e32 v189, 16, v153
	v_and_b32_e32 v190, 0xffff0000, v153
	v_mul_f32_e32 v195, 0xbfb8aa3b, v187
	v_exp_f32_e32 v195, v195
	s_nop 0
	v_add_f32_e32 v195, 1.0, v195
	v_div_scale_f32 v191, s[52:53], v195, v195, v187
	v_rcp_f32_e32 v192, v191
	s_nop 0
	v_fma_f32 v193, -v191, v192, 1.0
	v_fmac_f32_e32 v192, v193, v192
	v_div_scale_f32 v193, vcc, v187, v195, v187
	v_mul_f32_e32 v194, v193, v192
	v_fma_f32 v196, -v191, v194, v193
	v_fmac_f32_e32 v194, v196, v192
	v_fma_f32 v191, -v191, v194, v193
	v_div_fmas_f32 v191, v191, v192, v194
	v_div_fixup_f32 v191, v191, v195, v187
	v_mul_f32_e32 v32, v32, v191
	v_mul_f32_e32 v195, 0xbfb8aa3b, v188
	v_exp_f32_e32 v195, v195
	s_nop 0
	v_add_f32_e32 v195, 1.0, v195
	v_div_scale_f32 v191, s[52:53], v195, v195, v188
	v_rcp_f32_e32 v192, v191
	s_nop 0
	v_fma_f32 v193, -v191, v192, 1.0
	v_fmac_f32_e32 v192, v193, v192
	v_div_scale_f32 v193, vcc, v188, v195, v188
	v_mul_f32_e32 v194, v193, v192
	v_fma_f32 v196, -v191, v194, v193
	v_fmac_f32_e32 v194, v196, v192
	v_fma_f32 v191, -v191, v194, v193
	v_div_fmas_f32 v191, v191, v192, v194
	v_div_fixup_f32 v191, v191, v195, v188
	v_mul_f32_e32 v33, v33, v191
	v_mul_f32_e32 v195, 0xbfb8aa3b, v189
	v_exp_f32_e32 v195, v195
	s_nop 0
	v_add_f32_e32 v195, 1.0, v195
	v_div_scale_f32 v191, s[52:53], v195, v195, v189
	v_rcp_f32_e32 v192, v191
	s_nop 0
	v_fma_f32 v193, -v191, v192, 1.0
	v_fmac_f32_e32 v192, v193, v192
	v_div_scale_f32 v193, vcc, v189, v195, v189
	v_mul_f32_e32 v194, v193, v192
	v_fma_f32 v196, -v191, v194, v193
	v_fmac_f32_e32 v194, v196, v192
	v_fma_f32 v191, -v191, v194, v193
	v_div_fmas_f32 v191, v191, v192, v194
	v_div_fixup_f32 v191, v191, v195, v189
	v_mul_f32_e32 v34, v34, v191
	v_mul_f32_e32 v195, 0xbfb8aa3b, v190
	v_exp_f32_e32 v195, v195
	s_nop 0
	v_add_f32_e32 v195, 1.0, v195
	v_div_scale_f32 v191, s[52:53], v195, v195, v190
	v_rcp_f32_e32 v192, v191
	s_nop 0
	v_fma_f32 v193, -v191, v192, 1.0
	v_fmac_f32_e32 v192, v193, v192
	v_div_scale_f32 v193, vcc, v190, v195, v190
	v_mul_f32_e32 v194, v193, v192
	v_fma_f32 v196, -v191, v194, v193
	v_fmac_f32_e32 v194, v196, v192
	v_fma_f32 v191, -v191, v194, v193
	v_div_fmas_f32 v191, v191, v192, v194
	v_div_fixup_f32 v191, v191, v195, v190
	v_mul_f32_e32 v35, v35, v191
	v_bfe_u32 v191, v32, 16, 1
	v_bfe_u32 v192, v33, 16, 1
	v_bfe_u32 v193, v34, 16, 1
	v_bfe_u32 v194, v35, 16, 1
	v_add3_u32 v32, v32, v191, s69
	v_add3_u32 v33, v33, v192, s69
	v_add3_u32 v34, v34, v193, s69
	v_add3_u32 v35, v35, v194, s69
	v_lshrrev_b32_e32 v32, 16, v32
	v_lshrrev_b32_e32 v34, 16, v34
	v_and_or_b32 v198, v33, s34, v32
	v_and_or_b32 v199, v35, s34, v34
	global_store_dwordx2 v176, v[198:199], s[8:9]
	s_nop 1
	ds_read_b128 v[36:39], v175 offset:46080
	s_waitcnt lgkmcnt(0)
	v_mul_f32_e32 v185, v36, v36
	v_fmac_f32_e32 v185, v37, v37
	v_fmac_f32_e32 v185, v38, v38
	v_fmac_f32_e32 v185, v39, v39
	s_nop 1
	v_add_f32_dpp v185, v185, v185 quad_perm:[1,0,3,2] row_mask:0xf bank_mask:0xf
	s_nop 1
	v_add_f32_dpp v185, v185, v185 quad_perm:[2,3,0,1] row_mask:0xf bank_mask:0xf
	s_nop 1
	v_add_f32_dpp v185, v185, v185 row_half_mirror row_mask:0xf bank_mask:0xf
	s_nop 1
	v_add_f32_dpp v185, v185, v185 row_mirror row_mask:0xf bank_mask:0xf
	v_mov_b32_e32 v186, 0x358637bd
	v_fmac_f32_e32 v186, 0x3c800000, v185
	v_rsq_f32_e32 v186, v186
	s_nop 0
	v_mul_f32_e32 v36, v36, v186
	v_mul_f32_e32 v37, v37, v186
	v_mul_f32_e32 v38, v38, v186
	v_mul_f32_e32 v39, v39, v186
	v_mul_f32_e32 v36, v36, v160
	v_mul_f32_e32 v37, v37, v161
	v_mul_f32_e32 v38, v38, v162
	v_mul_f32_e32 v39, v39, v163
	v_lshlrev_b32_e32 v187, 16, v154
	v_and_b32_e32 v188, 0xffff0000, v154
	v_lshlrev_b32_e32 v189, 16, v155
	v_and_b32_e32 v190, 0xffff0000, v155
	v_mul_f32_e32 v195, 0xbfb8aa3b, v187
	v_exp_f32_e32 v195, v195
	s_nop 0
	v_add_f32_e32 v195, 1.0, v195
	v_div_scale_f32 v191, s[52:53], v195, v195, v187
	v_rcp_f32_e32 v192, v191
	s_nop 0
	v_fma_f32 v193, -v191, v192, 1.0
	v_fmac_f32_e32 v192, v193, v192
	v_div_scale_f32 v193, vcc, v187, v195, v187
	v_mul_f32_e32 v194, v193, v192
	v_fma_f32 v196, -v191, v194, v193
	v_fmac_f32_e32 v194, v196, v192
	v_fma_f32 v191, -v191, v194, v193
	v_div_fmas_f32 v191, v191, v192, v194
	v_div_fixup_f32 v191, v191, v195, v187
	v_mul_f32_e32 v36, v36, v191
	v_mul_f32_e32 v195, 0xbfb8aa3b, v188
	v_exp_f32_e32 v195, v195
	s_nop 0
	v_add_f32_e32 v195, 1.0, v195
	v_div_scale_f32 v191, s[52:53], v195, v195, v188
	v_rcp_f32_e32 v192, v191
	s_nop 0
	v_fma_f32 v193, -v191, v192, 1.0
	v_fmac_f32_e32 v192, v193, v192
	v_div_scale_f32 v193, vcc, v188, v195, v188
	v_mul_f32_e32 v194, v193, v192
	v_fma_f32 v196, -v191, v194, v193
	v_fmac_f32_e32 v194, v196, v192
	v_fma_f32 v191, -v191, v194, v193
	v_div_fmas_f32 v191, v191, v192, v194
	v_div_fixup_f32 v191, v191, v195, v188
	v_mul_f32_e32 v37, v37, v191
	v_mul_f32_e32 v195, 0xbfb8aa3b, v189
	v_exp_f32_e32 v195, v195
	s_nop 0
	v_add_f32_e32 v195, 1.0, v195
	v_div_scale_f32 v191, s[52:53], v195, v195, v189
	v_rcp_f32_e32 v192, v191
	s_nop 0
	v_fma_f32 v193, -v191, v192, 1.0
	v_fmac_f32_e32 v192, v193, v192
	v_div_scale_f32 v193, vcc, v189, v195, v189
	v_mul_f32_e32 v194, v193, v192
	v_fma_f32 v196, -v191, v194, v193
	v_fmac_f32_e32 v194, v196, v192
	v_fma_f32 v191, -v191, v194, v193
	v_div_fmas_f32 v191, v191, v192, v194
	v_div_fixup_f32 v191, v191, v195, v189
	v_mul_f32_e32 v38, v38, v191
	v_mul_f32_e32 v195, 0xbfb8aa3b, v190
	v_exp_f32_e32 v195, v195
	s_nop 0
	v_add_f32_e32 v195, 1.0, v195
	v_div_scale_f32 v191, s[52:53], v195, v195, v190
	v_rcp_f32_e32 v192, v191
	s_nop 0
	v_fma_f32 v193, -v191, v192, 1.0
	v_fmac_f32_e32 v192, v193, v192
	v_div_scale_f32 v193, vcc, v190, v195, v190
	v_mul_f32_e32 v194, v193, v192
	v_fma_f32 v196, -v191, v194, v193
	v_fmac_f32_e32 v194, v196, v192
	v_fma_f32 v191, -v191, v194, v193
	v_div_fmas_f32 v191, v191, v192, v194
	v_div_fixup_f32 v191, v191, v195, v190
	v_mul_f32_e32 v39, v39, v191
	v_bfe_u32 v191, v36, 16, 1
	v_bfe_u32 v192, v37, 16, 1
	v_bfe_u32 v193, v38, 16, 1
	v_bfe_u32 v194, v39, 16, 1
	v_add3_u32 v36, v36, v191, s69
	v_add3_u32 v37, v37, v192, s69
	v_add3_u32 v38, v38, v193, s69
	v_add3_u32 v39, v39, v194, s69
	v_lshrrev_b32_e32 v36, 16, v36
	v_lshrrev_b32_e32 v38, 16, v38
	v_and_or_b32 v198, v37, s34, v36
	v_and_or_b32 v199, v39, s34, v38
	global_store_dwordx2 v177, v[198:199], s[8:9]
	s_nop 1
	ds_read_b128 v[40:43], v175 offset:50176
	s_waitcnt lgkmcnt(0)
	v_mul_f32_e32 v185, v40, v40
	v_fmac_f32_e32 v185, v41, v41
	v_fmac_f32_e32 v185, v42, v42
	v_fmac_f32_e32 v185, v43, v43
	s_nop 1
	v_add_f32_dpp v185, v185, v185 quad_perm:[1,0,3,2] row_mask:0xf bank_mask:0xf
	s_nop 1
	v_add_f32_dpp v185, v185, v185 quad_perm:[2,3,0,1] row_mask:0xf bank_mask:0xf
	s_nop 1
	v_add_f32_dpp v185, v185, v185 row_half_mirror row_mask:0xf bank_mask:0xf
	s_nop 1
	v_add_f32_dpp v185, v185, v185 row_mirror row_mask:0xf bank_mask:0xf
	v_mov_b32_e32 v186, 0x358637bd
	v_fmac_f32_e32 v186, 0x3c800000, v185
	v_rsq_f32_e32 v186, v186
	s_nop 0
	v_mul_f32_e32 v40, v40, v186
	v_mul_f32_e32 v41, v41, v186
	v_mul_f32_e32 v42, v42, v186
	v_mul_f32_e32 v43, v43, v186
	v_mul_f32_e32 v40, v40, v160
	v_mul_f32_e32 v41, v41, v161
	v_mul_f32_e32 v42, v42, v162
	v_mul_f32_e32 v43, v43, v163
	v_lshlrev_b32_e32 v187, 16, v156
	v_and_b32_e32 v188, 0xffff0000, v156
	v_lshlrev_b32_e32 v189, 16, v157
	v_and_b32_e32 v190, 0xffff0000, v157
	v_mul_f32_e32 v195, 0xbfb8aa3b, v187
	v_exp_f32_e32 v195, v195
	s_nop 0
	v_add_f32_e32 v195, 1.0, v195
	v_div_scale_f32 v191, s[52:53], v195, v195, v187
	v_rcp_f32_e32 v192, v191
	s_nop 0
	v_fma_f32 v193, -v191, v192, 1.0
	v_fmac_f32_e32 v192, v193, v192
	v_div_scale_f32 v193, vcc, v187, v195, v187
	v_mul_f32_e32 v194, v193, v192
	v_fma_f32 v196, -v191, v194, v193
	v_fmac_f32_e32 v194, v196, v192
	v_fma_f32 v191, -v191, v194, v193
	v_div_fmas_f32 v191, v191, v192, v194
	v_div_fixup_f32 v191, v191, v195, v187
	v_mul_f32_e32 v40, v40, v191
	v_mul_f32_e32 v195, 0xbfb8aa3b, v188
	v_exp_f32_e32 v195, v195
	s_nop 0
	v_add_f32_e32 v195, 1.0, v195
	v_div_scale_f32 v191, s[52:53], v195, v195, v188
	v_rcp_f32_e32 v192, v191
	s_nop 0
	v_fma_f32 v193, -v191, v192, 1.0
	v_fmac_f32_e32 v192, v193, v192
	v_div_scale_f32 v193, vcc, v188, v195, v188
	v_mul_f32_e32 v194, v193, v192
	v_fma_f32 v196, -v191, v194, v193
	v_fmac_f32_e32 v194, v196, v192
	v_fma_f32 v191, -v191, v194, v193
	v_div_fmas_f32 v191, v191, v192, v194
	v_div_fixup_f32 v191, v191, v195, v188
	v_mul_f32_e32 v41, v41, v191
	v_mul_f32_e32 v195, 0xbfb8aa3b, v189
	v_exp_f32_e32 v195, v195
	s_nop 0
	v_add_f32_e32 v195, 1.0, v195
	v_div_scale_f32 v191, s[52:53], v195, v195, v189
	v_rcp_f32_e32 v192, v191
	s_nop 0
	v_fma_f32 v193, -v191, v192, 1.0
	v_fmac_f32_e32 v192, v193, v192
	v_div_scale_f32 v193, vcc, v189, v195, v189
	v_mul_f32_e32 v194, v193, v192
	v_fma_f32 v196, -v191, v194, v193
	v_fmac_f32_e32 v194, v196, v192
	v_fma_f32 v191, -v191, v194, v193
	v_div_fmas_f32 v191, v191, v192, v194
	v_div_fixup_f32 v191, v191, v195, v189
	v_mul_f32_e32 v42, v42, v191
	v_mul_f32_e32 v195, 0xbfb8aa3b, v190
	v_exp_f32_e32 v195, v195
	s_nop 0
	v_add_f32_e32 v195, 1.0, v195
	v_div_scale_f32 v191, s[52:53], v195, v195, v190
	v_rcp_f32_e32 v192, v191
	s_nop 0
	v_fma_f32 v193, -v191, v192, 1.0
	v_fmac_f32_e32 v192, v193, v192
	v_div_scale_f32 v193, vcc, v190, v195, v190
	v_mul_f32_e32 v194, v193, v192
	v_fma_f32 v196, -v191, v194, v193
	v_fmac_f32_e32 v194, v196, v192
	v_fma_f32 v191, -v191, v194, v193
	v_div_fmas_f32 v191, v191, v192, v194
	v_div_fixup_f32 v191, v191, v195, v190
	v_mul_f32_e32 v43, v43, v191
	v_bfe_u32 v191, v40, 16, 1
	v_bfe_u32 v192, v41, 16, 1
	v_bfe_u32 v193, v42, 16, 1
	v_bfe_u32 v194, v43, 16, 1
	v_add3_u32 v40, v40, v191, s69
	v_add3_u32 v41, v41, v192, s69
	v_add3_u32 v42, v42, v193, s69
	v_add3_u32 v43, v43, v194, s69
	v_lshrrev_b32_e32 v40, 16, v40
	v_lshrrev_b32_e32 v42, 16, v42
	v_and_or_b32 v198, v41, s34, v40
	v_and_or_b32 v199, v43, s34, v42
	global_store_dwordx2 v178, v[198:199], s[8:9]
	s_nop 1
	ds_read_b128 v[44:47], v175 offset:54272
	s_waitcnt lgkmcnt(0)
	v_mul_f32_e32 v185, v44, v44
	v_fmac_f32_e32 v185, v45, v45
	v_fmac_f32_e32 v185, v46, v46
	v_fmac_f32_e32 v185, v47, v47
	s_nop 1
	v_add_f32_dpp v185, v185, v185 quad_perm:[1,0,3,2] row_mask:0xf bank_mask:0xf
	s_nop 1
	v_add_f32_dpp v185, v185, v185 quad_perm:[2,3,0,1] row_mask:0xf bank_mask:0xf
	s_nop 1
	v_add_f32_dpp v185, v185, v185 row_half_mirror row_mask:0xf bank_mask:0xf
	s_nop 1
	v_add_f32_dpp v185, v185, v185 row_mirror row_mask:0xf bank_mask:0xf
	v_mov_b32_e32 v186, 0x358637bd
	v_fmac_f32_e32 v186, 0x3c800000, v185
	v_rsq_f32_e32 v186, v186
	s_nop 0
	v_mul_f32_e32 v44, v44, v186
	v_mul_f32_e32 v45, v45, v186
	v_mul_f32_e32 v46, v46, v186
	v_mul_f32_e32 v47, v47, v186
	v_mul_f32_e32 v44, v44, v160
	v_mul_f32_e32 v45, v45, v161
	v_mul_f32_e32 v46, v46, v162
	v_mul_f32_e32 v47, v47, v163
	v_lshlrev_b32_e32 v187, 16, v158
	v_and_b32_e32 v188, 0xffff0000, v158
	v_lshlrev_b32_e32 v189, 16, v159
	v_and_b32_e32 v190, 0xffff0000, v159
	v_mul_f32_e32 v195, 0xbfb8aa3b, v187
	v_exp_f32_e32 v195, v195
	s_nop 0
	v_add_f32_e32 v195, 1.0, v195
	v_div_scale_f32 v191, s[52:53], v195, v195, v187
	v_rcp_f32_e32 v192, v191
	s_nop 0
	v_fma_f32 v193, -v191, v192, 1.0
	v_fmac_f32_e32 v192, v193, v192
	v_div_scale_f32 v193, vcc, v187, v195, v187
	v_mul_f32_e32 v194, v193, v192
	v_fma_f32 v196, -v191, v194, v193
	v_fmac_f32_e32 v194, v196, v192
	v_fma_f32 v191, -v191, v194, v193
	v_div_fmas_f32 v191, v191, v192, v194
	v_div_fixup_f32 v191, v191, v195, v187
	v_mul_f32_e32 v44, v44, v191
	v_mul_f32_e32 v195, 0xbfb8aa3b, v188
	v_exp_f32_e32 v195, v195
	s_nop 0
	v_add_f32_e32 v195, 1.0, v195
	v_div_scale_f32 v191, s[52:53], v195, v195, v188
	v_rcp_f32_e32 v192, v191
	s_nop 0
	v_fma_f32 v193, -v191, v192, 1.0
	v_fmac_f32_e32 v192, v193, v192
	v_div_scale_f32 v193, vcc, v188, v195, v188
	v_mul_f32_e32 v194, v193, v192
	v_fma_f32 v196, -v191, v194, v193
	v_fmac_f32_e32 v194, v196, v192
	v_fma_f32 v191, -v191, v194, v193
	v_div_fmas_f32 v191, v191, v192, v194
	v_div_fixup_f32 v191, v191, v195, v188
	v_mul_f32_e32 v45, v45, v191
	v_mul_f32_e32 v195, 0xbfb8aa3b, v189
	v_exp_f32_e32 v195, v195
	s_nop 0
	v_add_f32_e32 v195, 1.0, v195
	v_div_scale_f32 v191, s[52:53], v195, v195, v189
	v_rcp_f32_e32 v192, v191
	s_nop 0
	v_fma_f32 v193, -v191, v192, 1.0
	v_fmac_f32_e32 v192, v193, v192
	v_div_scale_f32 v193, vcc, v189, v195, v189
	v_mul_f32_e32 v194, v193, v192
	v_fma_f32 v196, -v191, v194, v193
	v_fmac_f32_e32 v194, v196, v192
	v_fma_f32 v191, -v191, v194, v193
	v_div_fmas_f32 v191, v191, v192, v194
	v_div_fixup_f32 v191, v191, v195, v189
	v_mul_f32_e32 v46, v46, v191
	v_mul_f32_e32 v195, 0xbfb8aa3b, v190
	v_exp_f32_e32 v195, v195
	s_nop 0
	v_add_f32_e32 v195, 1.0, v195
	v_div_scale_f32 v191, s[52:53], v195, v195, v190
	v_rcp_f32_e32 v192, v191
	s_nop 0
	v_fma_f32 v193, -v191, v192, 1.0
	v_fmac_f32_e32 v192, v193, v192
	v_div_scale_f32 v193, vcc, v190, v195, v190
	v_mul_f32_e32 v194, v193, v192
	v_fma_f32 v196, -v191, v194, v193
	v_fmac_f32_e32 v194, v196, v192
	v_fma_f32 v191, -v191, v194, v193
	v_div_fmas_f32 v191, v191, v192, v194
	v_div_fixup_f32 v191, v191, v195, v190
	v_mul_f32_e32 v47, v47, v191
	v_bfe_u32 v191, v44, 16, 1
	v_bfe_u32 v192, v45, 16, 1
	v_bfe_u32 v193, v46, 16, 1
	v_bfe_u32 v194, v47, 16, 1
	v_add3_u32 v44, v44, v191, s69
	v_add3_u32 v45, v45, v192, s69
	v_add3_u32 v46, v46, v193, s69
	v_add3_u32 v47, v47, v194, s69
	v_lshrrev_b32_e32 v44, 16, v44
	v_lshrrev_b32_e32 v46, 16, v46
	v_and_or_b32 v198, v45, s34, v44
	v_and_or_b32 v199, v47, s34, v46
	global_store_dwordx2 v179, v[198:199], s[8:9]
	s_nop 1
	s_waitcnt vmcnt(4)
	s_branch .Ldq_epid
.Ldq_epi3:
	ds_read_b128 v[44:47], v175 offset:54272
	s_waitcnt lgkmcnt(0)
	v_mul_f32_e32 v185, v44, v44
	v_fmac_f32_e32 v185, v45, v45
	v_fmac_f32_e32 v185, v46, v46
	v_fmac_f32_e32 v185, v47, v47
	s_nop 1
	v_add_f32_dpp v185, v185, v185 quad_perm:[1,0,3,2] row_mask:0xf bank_mask:0xf
	s_nop 1
	v_add_f32_dpp v185, v185, v185 quad_perm:[2,3,0,1] row_mask:0xf bank_mask:0xf
	s_nop 1
	v_add_f32_dpp v185, v185, v185 row_half_mirror row_mask:0xf bank_mask:0xf
	s_nop 1
	v_add_f32_dpp v185, v185, v185 row_mirror row_mask:0xf bank_mask:0xf
	v_mov_b32_e32 v186, 0x358637bd
	v_fmac_f32_e32 v186, 0x3c800000, v185
	v_rsq_f32_e32 v186, v186
	s_nop 0
	v_mul_f32_e32 v44, v44, v186
	v_mul_f32_e32 v45, v45, v186
	v_mul_f32_e32 v46, v46, v186
	v_mul_f32_e32 v47, v47, v186
	v_mul_f32_e32 v44, v44, v160
	v_mul_f32_e32 v45, v45, v161
	v_mul_f32_e32 v46, v46, v162
	v_mul_f32_e32 v47, v47, v163
	v_lshlrev_b32_e32 v187, 16, v158
	v_and_b32_e32 v188, 0xffff0000, v158
	v_lshlrev_b32_e32 v189, 16, v159
	v_and_b32_e32 v190, 0xffff0000, v159
	v_mul_f32_e32 v195, 0xbfb8aa3b, v187
	v_exp_f32_e32 v195, v195
	s_nop 0
	v_add_f32_e32 v195, 1.0, v195
	v_div_scale_f32 v191, s[52:53], v195, v195, v187
	v_rcp_f32_e32 v192, v191
	s_nop 0
	v_fma_f32 v193, -v191, v192, 1.0
	v_fmac_f32_e32 v192, v193, v192
	v_div_scale_f32 v193, vcc, v187, v195, v187
	v_mul_f32_e32 v194, v193, v192
	v_fma_f32 v196, -v191, v194, v193
	v_fmac_f32_e32 v194, v196, v192
	v_fma_f32 v191, -v191, v194, v193
	v_div_fmas_f32 v191, v191, v192, v194
	v_div_fixup_f32 v191, v191, v195, v187
	v_mul_f32_e32 v44, v44, v191
	v_mul_f32_e32 v195, 0xbfb8aa3b, v188
	v_exp_f32_e32 v195, v195
	s_nop 0
	v_add_f32_e32 v195, 1.0, v195
	v_div_scale_f32 v191, s[52:53], v195, v195, v188
	v_rcp_f32_e32 v192, v191
	s_nop 0
	v_fma_f32 v193, -v191, v192, 1.0
	v_fmac_f32_e32 v192, v193, v192
	v_div_scale_f32 v193, vcc, v188, v195, v188
	v_mul_f32_e32 v194, v193, v192
	v_fma_f32 v196, -v191, v194, v193
	v_fmac_f32_e32 v194, v196, v192
	v_fma_f32 v191, -v191, v194, v193
	v_div_fmas_f32 v191, v191, v192, v194
	v_div_fixup_f32 v191, v191, v195, v188
	v_mul_f32_e32 v45, v45, v191
	v_mul_f32_e32 v195, 0xbfb8aa3b, v189
	v_exp_f32_e32 v195, v195
	s_nop 0
	v_add_f32_e32 v195, 1.0, v195
	v_div_scale_f32 v191, s[52:53], v195, v195, v189
	v_rcp_f32_e32 v192, v191
	s_nop 0
	v_fma_f32 v193, -v191, v192, 1.0
	v_fmac_f32_e32 v192, v193, v192
	v_div_scale_f32 v193, vcc, v189, v195, v189
	v_mul_f32_e32 v194, v193, v192
	v_fma_f32 v196, -v191, v194, v193
	v_fmac_f32_e32 v194, v196, v192
	v_fma_f32 v191, -v191, v194, v193
	v_div_fmas_f32 v191, v191, v192, v194
	v_div_fixup_f32 v191, v191, v195, v189
	v_mul_f32_e32 v46, v46, v191
	v_mul_f32_e32 v195, 0xbfb8aa3b, v190
	v_exp_f32_e32 v195, v195
	s_nop 0
	v_add_f32_e32 v195, 1.0, v195
	v_div_scale_f32 v191, s[52:53], v195, v195, v190
	v_rcp_f32_e32 v192, v191
	s_nop 0
	v_fma_f32 v193, -v191, v192, 1.0
	v_fmac_f32_e32 v192, v193, v192
	v_div_scale_f32 v193, vcc, v190, v195, v190
	v_mul_f32_e32 v194, v193, v192
	v_fma_f32 v196, -v191, v194, v193
	v_fmac_f32_e32 v194, v196, v192
	v_fma_f32 v191, -v191, v194, v193
	v_div_fmas_f32 v191, v191, v192, v194
	v_div_fixup_f32 v191, v191, v195, v190
	v_mul_f32_e32 v47, v47, v191
	v_bfe_u32 v191, v44, 16, 1
	v_bfe_u32 v192, v45, 16, 1
	v_bfe_u32 v193, v46, 16, 1
	v_bfe_u32 v194, v47, 16, 1
	v_add3_u32 v44, v44, v191, s69
	v_add3_u32 v45, v45, v192, s69
	v_add3_u32 v46, v46, v193, s69
	v_add3_u32 v47, v47, v194, s69
	v_lshrrev_b32_e32 v44, 16, v44
	v_lshrrev_b32_e32 v46, 16, v46
	v_and_or_b32 v198, v45, s34, v44
	v_and_or_b32 v199, v47, s34, v46
	global_store_dwordx2 v179, v[198:199], s[8:9]
	s_nop 1
	s_waitcnt vmcnt(1)
.Ldq_epid:
	v_mov_b32_e32 v152, v204
	v_mov_b32_e32 v153, v205
	v_mov_b32_e32 v154, v206
	v_mov_b32_e32 v155, v207
	v_mov_b32_e32 v156, v208
	v_mov_b32_e32 v157, v209
	v_mov_b32_e32 v158, v210
	v_mov_b32_e32 v159, v211
	v_mov_b32_e32 v164, v212
	s_add_u32 s8, s8, 0x20000
	s_addc_u32 s9, s9, 0
	s_add_u32 s12, s12, 1
	s_cmp_lg_u32 s12, 33
	s_cbranch_scc1 .Ldq_loop
	global_store_dword v173, v0, s[30:31] offset:0
	global_store_dword v173, v1, s[30:31] offset:256
	global_store_dword v173, v2, s[30:31] offset:512
	global_store_dword v173, v3, s[30:31] offset:768
	global_store_dword v173, v4, s[30:31] offset:2048
	global_store_dword v173, v5, s[30:31] offset:2304
	global_store_dword v173, v6, s[30:31] offset:2560
	global_store_dword v173, v7, s[30:31] offset:2816
	global_store_dword v184, v8, s[30:31] offset:0
	global_store_dword v184, v9, s[30:31] offset:256
	global_store_dword v184, v10, s[30:31] offset:512
	global_store_dword v184, v11, s[30:31] offset:768
	global_store_dword v184, v12, s[30:31] offset:2048
	global_store_dword v184, v13, s[30:31] offset:2304
	global_store_dword v184, v14, s[30:31] offset:2560
	global_store_dword v184, v15, s[30:31] offset:2816
	s_waitcnt vmcnt(0) lgkmcnt(0)
	s_barrier
	s_branch .LBB0_527
